# first mixer phase pooling rebalanced: the seven-row attention workgroups do no pooling, workgroups 0..7 lose their third round; 24 lightly loaded workgroups adopt those item pairs
# baseline (speedup 1.0000x reference)
.LBB0_204:
	s_andn2_b64 vcc, exec, s[0:1]
	s_cbranch_vccnz .LBB0_349
	s_and_b64 s[0:1], s[50:51], exec
	s_movk_i32 s0, 0x410
	s_cselect_b32 s16, s0, 0x400
	s_mov_b32 s3, -1
	v_readlane_b32 s2, v252, 2
	s_cmp_eq_u32 s2, 0x100
	s_cbranch_scc0 .Lpl_done
	v_readlane_b32 s2, v254, 58
	s_and_b32 s12, s2, -2
	s_cmp_eq_u32 s12, 64
	s_cbranch_scc1 .Lpl_heavy
	s_cmp_eq_u32 s12, 0x7c
	s_cbranch_scc1 .Lpl_heavy
	s_cmp_eq_u32 s12, 0xbe
	s_cbranch_scc1 .Lpl_heavy
	s_cmp_eq_u32 s12, 0xfa
	s_cbranch_scc1 .Lpl_heavy
	s_cmp_lt_u32 s2, 8
	s_cbranch_scc0 .Lpl_recv
	s_min_u32 s16, s16, 0x400
	s_branch .Lpl_done
.Lpl_recv:
	s_sub_u32 s12, s2, 0x7e
	s_cmp_lt_u32 s12, 24
	s_cbranch_scc0 .Lpl_done
	s_cmp_lt_u32 s12, 16
	s_cbranch_scc0 .Lpl_third
	s_and_b32 s13, s12, 7
	s_lshr_b32 s12, s12, 3
	s_lshl_b32 s12, s12, 9
	s_lshr_b32 s2, s13, 1
	s_and_b32 s13, s13, 1
	s_movk_i32 s3, 64
	s_cmp_eq_u32 s2, 1
	s_cselect_b32 s3, 0x7c, s3
	s_cmp_eq_u32 s2, 2
	s_cselect_b32 s3, 0xbe, s3
	s_cmp_eq_u32 s2, 3
	s_cselect_b32 s3, 0xfa, s3
	s_add_i32 s3, s3, s13
	s_lshl_b32 s3, s3, 1
	s_add_i32 s3, s3, s12
	s_branch .Lpl_done
.Lpl_third:
	s_sub_u32 s12, s12, 16
	s_lshl_b32 s3, s12, 1
	s_addk_i32 s3, 0x400
	s_cmp_lt_i32 s3, s16
	s_cselect_b32 s3, s3, -1
	s_branch .Lpl_done
.Lpl_heavy:
	s_mov_b32 s16, 0

.LBB0_207:
	s_waitcnt lgkmcnt(0)
	s_barrier
	ds_read_b128 v[2:5], v40 offset:20800
	ds_read_b128 v[6:9], v41 offset:30016
	ds_read_b128 v[10:13], v41 offset:32320
	ds_read_b128 v[16:19], v41 offset:34624
	ds_read_b128 v[48:51], v41 offset:36928
	s_waitcnt lgkmcnt(3)
	v_mfma_f32_16x16x32_bf16 v[6:9], v[6:9], v[2:5], 0
	v_lshlrev_b32_e32 v0, 2, v15
	v_readlane_b32 s0, v252, 20
	v_readlane_b32 s1, v252, 21
	s_waitcnt lgkmcnt(2)
	v_mfma_f32_16x16x32_bf16 v[10:13], v[10:13], v[2:5], 0
	v_mov_b32_e32 v31, v1
	s_waitcnt lgkmcnt(1)
	v_mfma_f32_16x16x32_bf16 v[16:19], v[16:19], v[2:5], 0
	s_waitcnt lgkmcnt(0)
	v_mfma_f32_16x16x32_bf16 v[2:5], v[48:51], v[2:5], 0
	ds_read_b128 v[48:51], v40 offset:20864
	ds_read_b128 v[52:55], v41 offset:30080
	s_waitcnt lgkmcnt(0)
	v_mfma_f32_16x16x32_bf16 v[52:55], v[52:55], v[48:51], v[6:9]
	s_nop 2
	ds_read_b128 v[6:9], v41 offset:32384
	s_waitcnt lgkmcnt(0)
	v_mfma_f32_16x16x32_bf16 v[10:13], v[6:9], v[48:51], v[10:13]
	ds_read_b128 v[6:9], v41 offset:34688
	s_waitcnt lgkmcnt(0)
	v_mfma_f32_16x16x32_bf16 v[6:9], v[6:9], v[48:51], v[16:19]
	s_nop 2
	ds_read_b128 v[16:19], v41 offset:36992
	s_waitcnt lgkmcnt(0)
	v_mfma_f32_16x16x32_bf16 v[2:5], v[16:19], v[48:51], v[2:5]
	v_lshl_add_u64 v[18:19], v[28:29], 0, v[0:1]
	v_lshlrev_b32_e32 v0, 1, v15
	v_lshl_add_u64 v[16:17], s[0:1], 0, v[0:1]
	v_or_b32_e32 v0, v14, v39
	v_cmp_gt_i32_e64 s[0:1], s37, v0
	s_nop 1
	v_cndmask_b32_e64 v14, 3, 1, s[0:1]
	v_add_u32_e32 v14, v14, v0
	v_ashrrev_i32_e32 v15, 31, v14
	v_lshlrev_b64 v[14:15], 11, v[14:15]
	v_lshl_add_u64 v[14:15], v[16:17], 0, v[14:15]
	v_lshl_add_u64 v[20:21], v[14:15], 0, v[30:31]
	global_load_dwordx4 v[14:17], v[18:19], off
	v_readlane_b32 s0, v252, 7
	v_readlane_b32 s1, v252, 8
	s_waitcnt vmcnt(0)
	v_mul_f32_e32 v0, v52, v14
	v_mul_f32_e32 v14, v53, v15
	v_mul_f32_e32 v15, v54, v16
	v_mul_f32_e32 v16, v55, v17
	v_cvt_pk_bf16_f32 v14, v0, v14
	v_cvt_pk_bf16_f32 v15, v15, v16
	global_store_dwordx2 v[20:21], v[14:15], off
	global_load_dwordx4 v[14:17], v[18:19], off offset:64
	s_waitcnt vmcnt(0)
	v_mul_f32_e32 v0, v10, v14
	v_mul_f32_e32 v10, v11, v15
	v_mul_f32_e32 v11, v12, v16
	v_mul_f32_e32 v12, v13, v17
	v_cvt_pk_bf16_f32 v10, v0, v10
	v_cvt_pk_bf16_f32 v11, v11, v12
	global_store_dwordx2 v[20:21], v[10:11], off offset:32
	global_load_dwordx4 v[10:13], v[18:19], off offset:128
	s_waitcnt vmcnt(0)
	v_mul_f32_e32 v0, v6, v10
	v_mul_f32_e32 v6, v7, v11
	v_mul_f32_e32 v7, v8, v12
	v_mul_f32_e32 v8, v9, v13
	v_cvt_pk_bf16_f32 v6, v0, v6
	v_cvt_pk_bf16_f32 v7, v7, v8
	global_store_dwordx2 v[20:21], v[6:7], off offset:64
	global_load_dwordx4 v[6:9], v[18:19], off offset:192
	s_waitcnt vmcnt(0)
	v_mul_f32_e32 v0, v2, v6
	v_mul_f32_e32 v2, v3, v7
	v_mul_f32_e32 v3, v4, v8
	v_mul_f32_e32 v4, v5, v9
	v_cvt_pk_bf16_f32 v2, v0, v2
	v_cvt_pk_bf16_f32 v3, v3, v4
	global_store_dwordx2 v[20:21], v[2:3], off offset:96
	s_barrier
	s_load_dword s0, s[0:1], 0x10
	s_waitcnt lgkmcnt(0)
	s_lshr_b32 s0, s0, 16
	s_cmp_lg_u32 s0, 0
	s_cselect_b64 s[0:1], -1, 0
	s_cmp_lg_u64 s[0:1], 0
	v_readlane_b32 s0, v252, 2
	s_addc_u32 s0, s0, 0
	s_lshl_b32 s0, s0, 1
	s_add_i32 s17, s0, s17
	v_readlane_b32 s1, v252, 3
	s_cmp_ge_i32 s17, s16
	s_cbranch_scc0 .LBB0_208
	v_readlane_b32 s0, v255, 23
	s_cmp_lt_i32 s0, 0
	s_cbranch_scc1 .LBB0_232
	s_mov_b32 s17, s0
	s_mov_b32 s16, 0
	s_mov_b32 s0, -1
	s_nop 0
	v_writelane_b32 v255, s0, 23
